# filler transposes read their f32 weights with nt loads (no L2 pollution next to the GEMM workgroups)
# speedup vs baseline: 1.0026x; 1.0026x over previous
; #define LAS __attribute__((address_space(3)))
; __device__ __forceinline__ unsigned pk2(float lo, float hi) { return pk2hw(lo, hi); }
; __device__ __forceinline__ void transpose_item(const float* W, int K, int N, bf16_t* WT, int drow0, LAS float* scr, int k0, int n0, int lane) {
; #pragma unroll 8
;     for (int i = 0; i < 32; ++i) { const int kk = 2 * i + (lane >> 5); scr[kk * 33 + (lane & 31)] = W[(size_t)(k0 + kk) * N + n0 + (lane & 31)]; }
;     asm volatile("s_waitcnt lgkmcnt(0)" ::: "memory");
;     const int c = lane & 7;
; #pragma unroll
;     for (int j = 0; j < 4; ++j) { const int n = (lane >> 3) + 8 * j; const LAS float* s = scr + (8 * c) * 33 + n;
;         u32x4 o; o.x = pk2(s[0 * 33], s[1 * 33]); o.y = pk2(s[2 * 33], s[3 * 33]); o.z = pk2(s[4 * 33], s[5 * 33]); o.w = pk2(s[6 * 33], s[7 * 33]);
;         *(u32x4*)(WT + (size_t)(drow0 + n) * K + k0 + 8 * c) = o; }
;     asm volatile("s_waitcnt lgkmcnt(0)" ::: "memory");
; __global__ void __launch_bounds__(NTHR, 2) fwd_kernel(Args a) {
;     ...
;                 if (r < IT_UP) { const int n0 = (r % 352) * 32, j = n0 < FF ? n0 : n0 - FF; transpose_item(a.in[I_WUP], DM, F2, WupT, (j >> 7) * 256 + (n0 < FF ? 0 : 128) + (j & 127), scr, (r / 352) * 64, n0, lane); continue; } r -= IT_UP;
.LBB0_954:
	s_lshl_b32 s22, s11, 1
	s_lshl_b32 s23, s20, 1
	v_or_b32_e32 v2, s22, v1
	v_or_b32_e32 v60, s23, v0
	s_add_i32 s24, s22, 4
	s_add_i32 s25, s23, 4
	s_add_i32 s26, s22, 8
	s_add_i32 s27, s23, 8
	s_add_i32 s28, s22, 12
	s_add_i32 s29, s23, 12
	s_add_i32 s30, s22, 16
	s_add_i32 s31, s23, 16
	s_add_i32 s33, s22, 20
	s_add_i32 s34, s23, 20
	s_add_i32 s35, s22, 24
	s_add_i32 s36, s23, 24
	s_add_i32 s22, s22, 28
	s_add_i32 s23, s23, 28
	v_add_u32_e32 v28, s4, v60
	v_or_b32_e32 v61, s24, v1
	v_or_b32_e32 v62, s25, v0
	v_or_b32_e32 v63, s26, v1
	v_or_b32_e32 v64, s27, v0
	v_or_b32_e32 v65, s28, v1
	v_or_b32_e32 v66, s29, v0
	v_or_b32_e32 v67, s30, v1
	v_or_b32_e32 v68, s31, v0
	v_or_b32_e32 v69, s33, v1
	v_or_b32_e32 v70, s34, v0
	v_or_b32_e32 v71, s35, v1
	v_or_b32_e32 v72, s36, v0
	v_or_b32_e32 v73, s22, v1
	v_or_b32_e32 v74, s23, v0
	v_add_u32_e32 v30, s5, v2
	v_mad_i64_i32 v[28:29], s[22:23], v28, s19, v[22:23]
	v_add_u32_e32 v34, s5, v61
	v_add_u32_e32 v32, s4, v62
	v_add_u32_e32 v38, s5, v63
	v_add_u32_e32 v36, s4, v64
	v_add_u32_e32 v42, s5, v65
	v_add_u32_e32 v40, s4, v66
	v_add_u32_e32 v46, s5, v67
	v_add_u32_e32 v44, s4, v68
	v_add_u32_e32 v50, s5, v69
	v_add_u32_e32 v48, s4, v70
	v_add_u32_e32 v54, s5, v71
	v_add_u32_e32 v52, s4, v72
	v_add_u32_e32 v58, s5, v73
	v_add_u32_e32 v56, s4, v74
	v_mad_i64_i32 v[30:31], s[22:23], v30, s19, v[22:23]
	v_mad_i64_i32 v[32:33], s[22:23], v32, s19, v[22:23]
	v_mad_i64_i32 v[34:35], s[22:23], v34, s19, v[22:23]
	v_mad_i64_i32 v[36:37], s[22:23], v36, s19, v[22:23]
	v_mad_i64_i32 v[38:39], s[22:23], v38, s19, v[22:23]
	v_mad_i64_i32 v[40:41], s[22:23], v40, s19, v[22:23]
	v_mad_i64_i32 v[42:43], s[22:23], v42, s19, v[22:23]
	v_mad_i64_i32 v[44:45], s[22:23], v44, s19, v[22:23]
	v_mad_i64_i32 v[46:47], s[22:23], v46, s19, v[22:23]
	v_mad_i64_i32 v[48:49], s[22:23], v48, s19, v[22:23]
	v_mad_i64_i32 v[50:51], s[22:23], v50, s19, v[22:23]
	v_mad_i64_i32 v[52:53], s[22:23], v52, s19, v[22:23]
	v_mad_i64_i32 v[54:55], s[22:23], v54, s19, v[22:23]
	v_mad_i64_i32 v[56:57], s[22:23], v56, s19, v[22:23]
	v_mad_i64_i32 v[58:59], s[22:23], v58, s19, v[22:23]
	global_load_dword v75, v[28:29], off nt
	global_load_dword v76, v[30:31], off nt
	global_load_dword v77, v[32:33], off nt
	global_load_dword v78, v[34:35], off nt
	global_load_dword v79, v[36:37], off nt
	global_load_dword v80, v[38:39], off nt
	global_load_dword v81, v[40:41], off nt
	global_load_dword v82, v[42:43], off nt
	global_load_dword v83, v[44:45], off nt
	global_load_dword v84, v[46:47], off nt
	global_load_dword v85, v[48:49], off nt
	global_load_dword v86, v[50:51], off nt
	global_load_dword v87, v[52:53], off nt
	global_load_dword v88, v[54:55], off nt
	global_load_dword v89, v[56:57], off nt
	global_load_dword v90, v[58:59], off nt
	s_add_i32 s20, s20, 16
	s_add_i32 s11, s11, 16
	s_add_i32 s21, s21, -16
	v_mad_u64_u32 v[28:29], s[22:23], v60, s18, v[6:7]
	s_cmp_lg_u32 s21, 0
	v_mad_u64_u32 v[30:31], s[22:23], v2, s18, v[6:7]
	v_mad_u64_u32 v[32:33], s[22:23], v62, s18, v[6:7]
	v_mad_u64_u32 v[34:35], s[22:23], v61, s18, v[6:7]
	v_mad_u64_u32 v[36:37], s[22:23], v64, s18, v[6:7]
	v_mad_u64_u32 v[38:39], s[22:23], v63, s18, v[6:7]
	v_mad_u64_u32 v[40:41], s[22:23], v66, s18, v[6:7]
	v_mad_u64_u32 v[42:43], s[22:23], v65, s18, v[6:7]
	v_mad_u64_u32 v[44:45], s[22:23], v68, s18, v[6:7]
	v_mad_u64_u32 v[46:47], s[22:23], v67, s18, v[6:7]
	v_mad_u64_u32 v[48:49], s[22:23], v70, s18, v[6:7]
	v_mad_u64_u32 v[50:51], s[22:23], v69, s18, v[6:7]
	v_mad_u64_u32 v[52:53], s[22:23], v72, s18, v[6:7]
	v_mad_u64_u32 v[54:55], s[22:23], v71, s18, v[6:7]
	v_mad_u64_u32 v[56:57], s[22:23], v74, s18, v[6:7]
	v_mad_u64_u32 v[58:59], s[22:23], v73, s18, v[6:7]
	s_waitcnt vmcnt(0)
	ds_write_b32 v28, v75
	ds_write_b32 v30, v76
	ds_write_b32 v32, v77
	ds_write_b32 v34, v78
	ds_write_b32 v36, v79
	ds_write_b32 v38, v80
	ds_write_b32 v40, v81
	ds_write_b32 v42, v82
	ds_write_b32 v44, v83
	ds_write_b32 v46, v84
	ds_write_b32 v48, v85
	ds_write_b32 v50, v86
	ds_write_b32 v52, v87
	ds_write_b32 v54, v88
	ds_write_b32 v56, v89
	ds_write_b32 v58, v90
	s_cbranch_scc1 .LBB0_954
	s_add_i32 s5, s10, 0xffffea00
	s_cmpk_lt_i32 s2, 0xb0
	s_cselect_b32 s2, s10, s5
	s_cselect_b32 s5, 0, 0x80
	s_lshl_b32 s10, s2, 1
	s_and_b32 s2, s2, 0x60
	s_waitcnt lgkmcnt(0)
	s_or_b32 s2, s2, s5
	s_and_b32 s5, s10, 0xffffff00
	ds_read2_b32 v[22:23], v24 offset0:33 offset1:41
	ds_read2_b32 v[32:33], v24 offset1:8
	ds_read2_b32 v[34:35], v24 offset0:66 offset1:74
	ds_read2_b32 v[36:37], v24 offset0:99 offset1:107
	ds_read2_b32 v[38:39], v24 offset0:132 offset1:140
	ds_read2_b32 v[40:41], v24 offset0:165 offset1:173
	ds_read2_b32 v[42:43], v24 offset0:198 offset1:206
	ds_read2_b32 v[44:45], v24 offset0:231 offset1:239
	s_or_b32 s2, s2, s5
	v_or_b32_e32 v48, s2, v7
	s_ashr_i32 s5, s4, 31
	v_ashrrev_i32_e32 v49, 31, v48
	v_lshl_add_u64 v[46:47], s[4:5], 1, v[8:9]
	v_lshlrev_b64 v[48:49], 12, v[48:49]
	s_waitcnt lgkmcnt(6)
	v_cvt_pk_bf16_f32 v28, v32, v22
	s_waitcnt lgkmcnt(4)
	v_cvt_pk_bf16_f32 v29, v34, v36
	s_waitcnt lgkmcnt(2)
	v_cvt_pk_bf16_f32 v30, v38, v40
	s_waitcnt lgkmcnt(0)
	v_cvt_pk_bf16_f32 v31, v42, v44
	v_lshl_add_u64 v[48:49], v[46:47], 0, v[48:49]
	v_or_b32_e32 v22, s2, v25
	global_store_dwordx4 v[48:49], v[28:31], off sc1
	s_mov_b64 s[4:5], 0
	s_nop 0
	v_cvt_pk_bf16_f32 v28, v33, v23
	v_ashrrev_i32_e32 v23, 31, v22
	v_cvt_pk_bf16_f32 v29, v35, v37
	v_cvt_pk_bf16_f32 v30, v39, v41
	v_cvt_pk_bf16_f32 v31, v43, v45
	v_lshlrev_b64 v[22:23], 12, v[22:23]
	ds_read2_b32 v[32:33], v24 offset0:49 offset1:57
	ds_read2_b32 v[34:35], v24 offset0:16 offset1:24
	ds_read2_b32 v[36:37], v24 offset0:82 offset1:90
	ds_read2_b32 v[38:39], v24 offset0:115 offset1:123
	ds_read2_b32 v[40:41], v24 offset0:148 offset1:156
	ds_read2_b32 v[42:43], v24 offset0:181 offset1:189
	ds_read2_b32 v[44:45], v24 offset0:214 offset1:222
	ds_read2_b32 v[48:49], v24 offset0:247 offset1:255
	v_lshl_add_u64 v[22:23], v[46:47], 0, v[22:23]
	global_store_dwordx4 v[22:23], v[28:31], off sc1
	v_or_b32_e32 v22, s2, v26
	v_ashrrev_i32_e32 v23, 31, v22
	v_lshlrev_b64 v[22:23], 12, v[22:23]
	s_waitcnt lgkmcnt(6)
	v_cvt_pk_bf16_f32 v28, v34, v32
	s_waitcnt lgkmcnt(4)
	v_cvt_pk_bf16_f32 v29, v36, v38
	s_waitcnt lgkmcnt(2)
	v_cvt_pk_bf16_f32 v30, v40, v42
	s_waitcnt lgkmcnt(0)
	v_cvt_pk_bf16_f32 v31, v44, v48
	v_lshl_add_u64 v[22:23], v[46:47], 0, v[22:23]
	global_store_dwordx4 v[22:23], v[28:31], off sc1
	v_or_b32_e32 v22, s2, v27
	v_ashrrev_i32_e32 v23, 31, v22
	v_lshlrev_b64 v[22:23], 12, v[22:23]
	v_cvt_pk_bf16_f32 v28, v35, v33
	v_cvt_pk_bf16_f32 v29, v37, v39
	v_cvt_pk_bf16_f32 v30, v41, v43
	v_cvt_pk_bf16_f32 v31, v45, v49
	v_lshl_add_u64 v[22:23], v[46:47], 0, v[22:23]
	global_store_dwordx4 v[22:23], v[28:31], off sc1
	s_waitcnt lgkmcnt(0)

; #define LAS __attribute__((address_space(3)))
; __device__ __forceinline__ void transpose_item(const float* W, int K, int N, bf16_t* WT, int drow0, LAS float* scr, int k0, int n0, int lane) {
; #pragma unroll 8
;     for (int i = 0; i < 32; ++i) { const int kk = 2 * i + (lane >> 5); scr[kk * 33 + (lane & 31)] = W[(size_t)(k0 + kk) * N + n0 + (lane & 31)]; }
; __global__ void __launch_bounds__(NTHR, 2) fwd_kernel(Args a) {
;     ...
;                     if (r < IT_GLA) { transpose_item(a.in[I_WGLA], VW, DM, WglaT, (r % 64) * 32, scr, (r / 64) * 64, (r % 64) * 32, lane); continue; } r -= IT_GLA;
;                     if (r < IT_FN) { transpose_item(a.in[I_WFN], FNW, DM, WfnT, (r % 64) * 32, scr, (r / 64) * 64, (r % 64) * 32, lane); continue; } r -= IT_FN;
;                     transpose_item(a.in[I_WOUT], DM, DM, WoT, (r % 64) * 32, scr, (r / 64) * 64, (r % 64) * 32, lane); continue; }
.LBB0_960:
	s_lshl_b32 s21, s5, 1
	s_lshl_b32 s22, s11, 1
	v_or_b32_e32 v2, s21, v1
	v_or_b32_e32 v60, s22, v0
	s_add_i32 s23, s21, 4
	s_add_i32 s24, s22, 4
	s_add_i32 s25, s21, 8
	s_add_i32 s26, s22, 8
	s_add_i32 s27, s21, 12
	s_add_i32 s28, s22, 12
	s_add_i32 s29, s21, 16
	s_add_i32 s30, s22, 16
	s_add_i32 s31, s21, 20
	s_add_i32 s33, s22, 20
	s_add_i32 s34, s21, 24
	s_add_i32 s35, s22, 24
	s_add_i32 s21, s21, 28
	s_add_i32 s22, s22, 28
	v_add_u32_e32 v30, s4, v60
	v_or_b32_e32 v61, s23, v1
	v_or_b32_e32 v62, s24, v0
	v_or_b32_e32 v63, s25, v1
	v_or_b32_e32 v64, s26, v0
	v_or_b32_e32 v65, s27, v1
	v_or_b32_e32 v66, s28, v0
	v_or_b32_e32 v67, s29, v1
	v_or_b32_e32 v68, s30, v0
	v_or_b32_e32 v69, s31, v1
	v_or_b32_e32 v70, s33, v0
	v_or_b32_e32 v71, s34, v1
	v_or_b32_e32 v72, s35, v0
	v_or_b32_e32 v73, s21, v1
	v_or_b32_e32 v74, s22, v0
	v_add_u32_e32 v28, s2, v2
	v_ashrrev_i32_e32 v31, 31, v30
	v_add_u32_e32 v32, s2, v61
	v_add_u32_e32 v34, s4, v62
	v_add_u32_e32 v36, s2, v63
	v_add_u32_e32 v38, s4, v64
	v_add_u32_e32 v40, s2, v65
	v_add_u32_e32 v42, s4, v66
	v_add_u32_e32 v44, s2, v67
	v_add_u32_e32 v46, s4, v68
	v_add_u32_e32 v48, s2, v69
	v_add_u32_e32 v50, s4, v70
	v_add_u32_e32 v52, s2, v71
	v_add_u32_e32 v54, s4, v72
	v_add_u32_e32 v56, s2, v73
	v_add_u32_e32 v58, s4, v74
	v_ashrrev_i32_e32 v29, 31, v28
	v_lshlrev_b64 v[30:31], 13, v[30:31]
	v_ashrrev_i32_e32 v35, 31, v34
	v_ashrrev_i32_e32 v33, 31, v32
	v_ashrrev_i32_e32 v39, 31, v38
	v_ashrrev_i32_e32 v37, 31, v36
	v_ashrrev_i32_e32 v43, 31, v42
	v_ashrrev_i32_e32 v41, 31, v40
	v_ashrrev_i32_e32 v47, 31, v46
	v_ashrrev_i32_e32 v45, 31, v44
	v_ashrrev_i32_e32 v51, 31, v50
	v_ashrrev_i32_e32 v49, 31, v48
	v_ashrrev_i32_e32 v55, 31, v54
	v_ashrrev_i32_e32 v53, 31, v52
	v_ashrrev_i32_e32 v59, 31, v58
	v_ashrrev_i32_e32 v57, 31, v56
	v_lshlrev_b64 v[28:29], 13, v[28:29]
	v_lshl_add_u64 v[30:31], v[22:23], 0, v[30:31]
	v_lshlrev_b64 v[32:33], 13, v[32:33]
	v_lshlrev_b64 v[34:35], 13, v[34:35]
	v_lshlrev_b64 v[36:37], 13, v[36:37]
	v_lshlrev_b64 v[38:39], 13, v[38:39]
	v_lshlrev_b64 v[40:41], 13, v[40:41]
	v_lshlrev_b64 v[42:43], 13, v[42:43]
	v_lshlrev_b64 v[44:45], 13, v[44:45]
	v_lshlrev_b64 v[46:47], 13, v[46:47]
	v_lshlrev_b64 v[48:49], 13, v[48:49]
	v_lshlrev_b64 v[50:51], 13, v[50:51]
	v_lshlrev_b64 v[52:53], 13, v[52:53]
	v_lshlrev_b64 v[54:55], 13, v[54:55]
	v_lshlrev_b64 v[56:57], 13, v[56:57]
	v_lshlrev_b64 v[58:59], 13, v[58:59]
	v_lshl_add_u64 v[28:29], v[22:23], 0, v[28:29]
	v_lshl_add_u64 v[34:35], v[22:23], 0, v[34:35]
	v_lshl_add_u64 v[32:33], v[22:23], 0, v[32:33]
	v_lshl_add_u64 v[38:39], v[22:23], 0, v[38:39]
	v_lshl_add_u64 v[36:37], v[22:23], 0, v[36:37]
	v_lshl_add_u64 v[42:43], v[22:23], 0, v[42:43]
	v_lshl_add_u64 v[40:41], v[22:23], 0, v[40:41]
	v_lshl_add_u64 v[46:47], v[22:23], 0, v[46:47]
	v_lshl_add_u64 v[44:45], v[22:23], 0, v[44:45]
	v_lshl_add_u64 v[50:51], v[22:23], 0, v[50:51]
	v_lshl_add_u64 v[48:49], v[22:23], 0, v[48:49]
	v_lshl_add_u64 v[54:55], v[22:23], 0, v[54:55]
	v_lshl_add_u64 v[52:53], v[22:23], 0, v[52:53]
	v_lshl_add_u64 v[58:59], v[22:23], 0, v[58:59]
	v_lshl_add_u64 v[56:57], v[22:23], 0, v[56:57]
	global_load_dword v75, v[30:31], off nt
	global_load_dword v76, v[28:29], off nt
	global_load_dword v77, v[34:35], off nt
	global_load_dword v78, v[32:33], off nt
	global_load_dword v79, v[38:39], off nt
	global_load_dword v80, v[36:37], off nt
	global_load_dword v81, v[42:43], off nt
	global_load_dword v82, v[40:41], off nt
	global_load_dword v83, v[46:47], off nt
	global_load_dword v84, v[44:45], off nt
	global_load_dword v85, v[50:51], off nt
	global_load_dword v86, v[48:49], off nt
	global_load_dword v87, v[54:55], off nt
	global_load_dword v88, v[52:53], off nt
	global_load_dword v89, v[58:59], off nt
	global_load_dword v90, v[56:57], off nt
	s_add_i32 s11, s11, 16
	s_add_i32 s5, s5, 16
	s_add_i32 s20, s20, -16
	v_mad_u64_u32 v[28:29], s[22:23], v60, s18, v[6:7]
	s_cmp_lg_u32 s20, 0
	v_mad_u64_u32 v[30:31], s[22:23], v2, s18, v[6:7]
	v_mad_u64_u32 v[32:33], s[22:23], v62, s18, v[6:7]
	v_mad_u64_u32 v[34:35], s[22:23], v61, s18, v[6:7]
	v_mad_u64_u32 v[36:37], s[22:23], v64, s18, v[6:7]
	v_mad_u64_u32 v[38:39], s[22:23], v63, s18, v[6:7]
	v_mad_u64_u32 v[40:41], s[22:23], v66, s18, v[6:7]
	v_mad_u64_u32 v[42:43], s[22:23], v65, s18, v[6:7]
	v_mad_u64_u32 v[44:45], s[22:23], v68, s18, v[6:7]
	v_mad_u64_u32 v[46:47], s[22:23], v67, s18, v[6:7]
	v_mad_u64_u32 v[48:49], s[22:23], v70, s18, v[6:7]
	v_mad_u64_u32 v[50:51], s[22:23], v69, s18, v[6:7]
	v_mad_u64_u32 v[52:53], s[22:23], v72, s18, v[6:7]
	v_mad_u64_u32 v[54:55], s[22:23], v71, s18, v[6:7]
	v_mad_u64_u32 v[56:57], s[22:23], v74, s18, v[6:7]
	v_mad_u64_u32 v[58:59], s[22:23], v73, s18, v[6:7]
	s_waitcnt vmcnt(0)
	ds_write_b32 v28, v75
	ds_write_b32 v30, v76
	ds_write_b32 v32, v77
	ds_write_b32 v34, v78
	ds_write_b32 v36, v79
	ds_write_b32 v38, v80
	ds_write_b32 v40, v81
	ds_write_b32 v42, v82
	ds_write_b32 v44, v83
	ds_write_b32 v46, v84
	ds_write_b32 v48, v85
	ds_write_b32 v50, v86
	ds_write_b32 v52, v87
	ds_write_b32 v54, v88
	ds_write_b32 v56, v89
	ds_write_b32 v58, v90
	s_cbranch_scc1 .LBB0_960
; #define LAS __attribute__((address_space(3)))
; __device__ __forceinline__ unsigned pk2(float lo, float hi) { return pk2hw(lo, hi); }
; __device__ __forceinline__ void transpose_item(const float* W, int K, int N, bf16_t* WT, int drow0, LAS float* scr, int k0, int n0, int lane) {
;     ...
;     asm volatile("s_waitcnt lgkmcnt(0)" ::: "memory");
;     const int c = lane & 7;
; #pragma unroll
;     for (int j = 0; j < 4; ++j) { const int n = (lane >> 3) + 8 * j; const LAS float* s = scr + (8 * c) * 33 + n;
;         u32x4 o; o.x = pk2(s[0 * 33], s[1 * 33]); o.y = pk2(s[2 * 33], s[3 * 33]); o.z = pk2(s[4 * 33], s[5 * 33]); o.w = pk2(s[6 * 33], s[7 * 33]);
;         *(u32x4*)(WT + (size_t)(drow0 + n) * K + k0 + 8 * c) = o; }
;     asm volatile("s_waitcnt lgkmcnt(0)" ::: "memory");
	s_waitcnt lgkmcnt(0)
	ds_read2_b32 v[22:23], v24 offset0:33 offset1:41
	ds_read2_b32 v[32:33], v24 offset1:8
	ds_read2_b32 v[34:35], v24 offset0:66 offset1:74
	ds_read2_b32 v[36:37], v24 offset0:99 offset1:107
	ds_read2_b32 v[38:39], v24 offset0:132 offset1:140
	ds_read2_b32 v[40:41], v24 offset0:165 offset1:173
	ds_read2_b32 v[42:43], v24 offset0:198 offset1:206
	ds_read2_b32 v[44:45], v24 offset0:231 offset1:239
	s_mov_b32 s5, s3
	v_or_b32_e32 v2, s10, v7
	v_lshl_add_u64 v[46:47], s[4:5], 1, v[12:13]
	v_lshlrev_b32_e32 v2, 12, v2
	s_waitcnt lgkmcnt(6)
	v_cvt_pk_bf16_f32 v28, v32, v22
	s_waitcnt lgkmcnt(4)
	v_cvt_pk_bf16_f32 v29, v34, v36
	s_waitcnt lgkmcnt(2)
	v_cvt_pk_bf16_f32 v30, v38, v40
	s_waitcnt lgkmcnt(0)
	v_cvt_pk_bf16_f32 v31, v42, v44
	v_lshl_add_u64 v[48:49], v[46:47], 0, v[2:3]
	global_store_dwordx4 v[48:49], v[28:31], off sc1
	v_or_b32_e32 v2, s10, v25
	v_lshlrev_b32_e32 v2, 12, v2
	v_cvt_pk_bf16_f32 v28, v33, v23
	v_cvt_pk_bf16_f32 v29, v35, v37
	v_cvt_pk_bf16_f32 v30, v39, v41
	v_cvt_pk_bf16_f32 v31, v43, v45
	ds_read2_b32 v[32:33], v24 offset0:49 offset1:57
	ds_read2_b32 v[34:35], v24 offset0:16 offset1:24
	ds_read2_b32 v[36:37], v24 offset0:82 offset1:90
	ds_read2_b32 v[38:39], v24 offset0:115 offset1:123
	ds_read2_b32 v[40:41], v24 offset0:148 offset1:156
	ds_read2_b32 v[42:43], v24 offset0:181 offset1:189
	ds_read2_b32 v[44:45], v24 offset0:214 offset1:222
	ds_read2_b32 v[48:49], v24 offset0:247 offset1:255
	v_lshl_add_u64 v[22:23], v[46:47], 0, v[2:3]
	v_or_b32_e32 v2, s10, v26
	v_lshlrev_b32_e32 v2, 12, v2
	global_store_dwordx4 v[22:23], v[28:31], off sc1
	v_lshl_add_u64 v[22:23], v[46:47], 0, v[2:3]
	v_or_b32_e32 v2, s10, v27
	s_waitcnt lgkmcnt(6)
	v_cvt_pk_bf16_f32 v28, v34, v32
	s_waitcnt lgkmcnt(4)
	v_cvt_pk_bf16_f32 v29, v36, v38
	s_waitcnt lgkmcnt(2)
	v_cvt_pk_bf16_f32 v30, v40, v42
	s_waitcnt lgkmcnt(0)
	v_cvt_pk_bf16_f32 v31, v44, v48
	v_lshlrev_b32_e32 v2, 12, v2
	global_store_dwordx4 v[22:23], v[28:31], off sc1
	v_lshl_add_u64 v[22:23], v[46:47], 0, v[2:3]
	s_mov_b64 s[4:5], 0
	v_cvt_pk_bf16_f32 v28, v35, v33
	v_cvt_pk_bf16_f32 v29, v37, v39
	v_cvt_pk_bf16_f32 v30, v41, v43
	v_cvt_pk_bf16_f32 v31, v45, v49
	global_store_dwordx4 v[22:23], v[28:31], off sc1
	s_waitcnt lgkmcnt(0)

; #define LAS __attribute__((address_space(3)))
; __device__ __forceinline__ void transpose_item(const float* W, int K, int N, bf16_t* WT, int drow0, LAS float* scr, int k0, int n0, int lane) {
; #pragma unroll 8
;     for (int i = 0; i < 32; ++i) { const int kk = 2 * i + (lane >> 5); scr[kk * 33 + (lane & 31)] = W[(size_t)(k0 + kk) * N + n0 + (lane & 31)]; }
; __global__ void __launch_bounds__(NTHR, 2) fwd_kernel(Args a) {
;     ...
;                     if (r < IT_GLA) { transpose_item(a.in[I_WGLA], VW, DM, WglaT, (r % 64) * 32, scr, (r / 64) * 64, (r % 64) * 32, lane); continue; } r -= IT_GLA;
;                     if (r < IT_FN) { transpose_item(a.in[I_WFN], FNW, DM, WfnT, (r % 64) * 32, scr, (r / 64) * 64, (r % 64) * 32, lane); continue; } r -= IT_FN;
;                     transpose_item(a.in[I_WOUT], DM, DM, WoT, (r % 64) * 32, scr, (r / 64) * 64, (r % 64) * 32, lane); continue; }
.LBB0_964:
	s_lshl_b32 s21, s5, 1
	s_lshl_b32 s22, s11, 1
	v_or_b32_e32 v2, s21, v1
	v_or_b32_e32 v60, s22, v0
	s_add_i32 s23, s21, 4
	s_add_i32 s24, s22, 4
	s_add_i32 s25, s21, 8
	s_add_i32 s26, s22, 8
	s_add_i32 s27, s21, 12
	s_add_i32 s28, s22, 12
	s_add_i32 s29, s21, 16
	s_add_i32 s30, s22, 16
	s_add_i32 s31, s21, 20
	s_add_i32 s33, s22, 20
	s_add_i32 s34, s21, 24
	s_add_i32 s35, s22, 24
	s_add_i32 s21, s21, 28
	s_add_i32 s22, s22, 28
	v_add_u32_e32 v30, s4, v60
	v_or_b32_e32 v61, s23, v1
	v_or_b32_e32 v62, s24, v0
	v_or_b32_e32 v63, s25, v1
	v_or_b32_e32 v64, s26, v0
	v_or_b32_e32 v65, s27, v1
	v_or_b32_e32 v66, s28, v0
	v_or_b32_e32 v67, s29, v1
	v_or_b32_e32 v68, s30, v0
	v_or_b32_e32 v69, s31, v1
	v_or_b32_e32 v70, s33, v0
	v_or_b32_e32 v71, s34, v1
	v_or_b32_e32 v72, s35, v0
	v_or_b32_e32 v73, s21, v1
	v_or_b32_e32 v74, s22, v0
	v_add_u32_e32 v28, s2, v2
	v_ashrrev_i32_e32 v31, 31, v30
	v_add_u32_e32 v32, s2, v61
	v_add_u32_e32 v34, s4, v62
	v_add_u32_e32 v36, s2, v63
	v_add_u32_e32 v38, s4, v64
	v_add_u32_e32 v40, s2, v65
	v_add_u32_e32 v42, s4, v66
	v_add_u32_e32 v44, s2, v67
	v_add_u32_e32 v46, s4, v68
	v_add_u32_e32 v48, s2, v69
	v_add_u32_e32 v50, s4, v70
	v_add_u32_e32 v52, s2, v71
	v_add_u32_e32 v54, s4, v72
	v_add_u32_e32 v56, s2, v73
	v_add_u32_e32 v58, s4, v74
	v_ashrrev_i32_e32 v29, 31, v28
	v_lshlrev_b64 v[30:31], 13, v[30:31]
	v_ashrrev_i32_e32 v35, 31, v34
	v_ashrrev_i32_e32 v33, 31, v32
	v_ashrrev_i32_e32 v39, 31, v38
	v_ashrrev_i32_e32 v37, 31, v36
	v_ashrrev_i32_e32 v43, 31, v42
	v_ashrrev_i32_e32 v41, 31, v40
	v_ashrrev_i32_e32 v47, 31, v46
	v_ashrrev_i32_e32 v45, 31, v44
	v_ashrrev_i32_e32 v51, 31, v50
	v_ashrrev_i32_e32 v49, 31, v48
	v_ashrrev_i32_e32 v55, 31, v54
	v_ashrrev_i32_e32 v53, 31, v52
	v_ashrrev_i32_e32 v59, 31, v58
	v_ashrrev_i32_e32 v57, 31, v56
	v_lshlrev_b64 v[28:29], 13, v[28:29]
	v_lshl_add_u64 v[30:31], v[22:23], 0, v[30:31]
	v_lshlrev_b64 v[32:33], 13, v[32:33]
	v_lshlrev_b64 v[34:35], 13, v[34:35]
	v_lshlrev_b64 v[36:37], 13, v[36:37]
	v_lshlrev_b64 v[38:39], 13, v[38:39]
	v_lshlrev_b64 v[40:41], 13, v[40:41]
	v_lshlrev_b64 v[42:43], 13, v[42:43]
	v_lshlrev_b64 v[44:45], 13, v[44:45]
	v_lshlrev_b64 v[46:47], 13, v[46:47]
	v_lshlrev_b64 v[48:49], 13, v[48:49]
	v_lshlrev_b64 v[50:51], 13, v[50:51]
	v_lshlrev_b64 v[52:53], 13, v[52:53]
	v_lshlrev_b64 v[54:55], 13, v[54:55]
	v_lshlrev_b64 v[56:57], 13, v[56:57]
	v_lshlrev_b64 v[58:59], 13, v[58:59]
	v_lshl_add_u64 v[28:29], v[22:23], 0, v[28:29]
	v_lshl_add_u64 v[34:35], v[22:23], 0, v[34:35]
	v_lshl_add_u64 v[32:33], v[22:23], 0, v[32:33]
	v_lshl_add_u64 v[38:39], v[22:23], 0, v[38:39]
	v_lshl_add_u64 v[36:37], v[22:23], 0, v[36:37]
	v_lshl_add_u64 v[42:43], v[22:23], 0, v[42:43]
	v_lshl_add_u64 v[40:41], v[22:23], 0, v[40:41]
	v_lshl_add_u64 v[46:47], v[22:23], 0, v[46:47]
	v_lshl_add_u64 v[44:45], v[22:23], 0, v[44:45]
	v_lshl_add_u64 v[50:51], v[22:23], 0, v[50:51]
	v_lshl_add_u64 v[48:49], v[22:23], 0, v[48:49]
	v_lshl_add_u64 v[54:55], v[22:23], 0, v[54:55]
	v_lshl_add_u64 v[52:53], v[22:23], 0, v[52:53]
	v_lshl_add_u64 v[58:59], v[22:23], 0, v[58:59]
	v_lshl_add_u64 v[56:57], v[22:23], 0, v[56:57]
	global_load_dword v75, v[30:31], off nt
	global_load_dword v76, v[28:29], off nt
	global_load_dword v77, v[34:35], off nt
	global_load_dword v78, v[32:33], off nt
	global_load_dword v79, v[38:39], off nt
	global_load_dword v80, v[36:37], off nt
	global_load_dword v81, v[42:43], off nt
	global_load_dword v82, v[40:41], off nt
	global_load_dword v83, v[46:47], off nt
	global_load_dword v84, v[44:45], off nt
	global_load_dword v85, v[50:51], off nt
	global_load_dword v86, v[48:49], off nt
	global_load_dword v87, v[54:55], off nt
	global_load_dword v88, v[52:53], off nt
	global_load_dword v89, v[58:59], off nt
	global_load_dword v90, v[56:57], off nt
	s_add_i32 s11, s11, 16
	s_add_i32 s5, s5, 16
	s_add_i32 s20, s20, -16
	v_mad_u64_u32 v[28:29], s[22:23], v60, s18, v[6:7]
	s_cmp_lg_u32 s20, 0
	v_mad_u64_u32 v[30:31], s[22:23], v2, s18, v[6:7]
	v_mad_u64_u32 v[32:33], s[22:23], v62, s18, v[6:7]
	v_mad_u64_u32 v[34:35], s[22:23], v61, s18, v[6:7]
	v_mad_u64_u32 v[36:37], s[22:23], v64, s18, v[6:7]
	v_mad_u64_u32 v[38:39], s[22:23], v63, s18, v[6:7]
	v_mad_u64_u32 v[40:41], s[22:23], v66, s18, v[6:7]
	v_mad_u64_u32 v[42:43], s[22:23], v65, s18, v[6:7]
	v_mad_u64_u32 v[44:45], s[22:23], v68, s18, v[6:7]
	v_mad_u64_u32 v[46:47], s[22:23], v67, s18, v[6:7]
	v_mad_u64_u32 v[48:49], s[22:23], v70, s18, v[6:7]
	v_mad_u64_u32 v[50:51], s[22:23], v69, s18, v[6:7]
	v_mad_u64_u32 v[52:53], s[22:23], v72, s18, v[6:7]
	v_mad_u64_u32 v[54:55], s[22:23], v71, s18, v[6:7]
	v_mad_u64_u32 v[56:57], s[22:23], v74, s18, v[6:7]
	v_mad_u64_u32 v[58:59], s[22:23], v73, s18, v[6:7]
	s_waitcnt vmcnt(0)
	ds_write_b32 v28, v75
	ds_write_b32 v30, v76
	ds_write_b32 v32, v77
	ds_write_b32 v34, v78
	ds_write_b32 v36, v79
	ds_write_b32 v38, v80
	ds_write_b32 v40, v81
	ds_write_b32 v42, v82
	ds_write_b32 v44, v83
	ds_write_b32 v46, v84
	ds_write_b32 v48, v85
	ds_write_b32 v50, v86
	ds_write_b32 v52, v87
	ds_write_b32 v54, v88
	ds_write_b32 v56, v89
	ds_write_b32 v58, v90
	s_cbranch_scc1 .LBB0_964
; #define LAS __attribute__((address_space(3)))
; __device__ __forceinline__ unsigned pk2(float lo, float hi) { return pk2hw(lo, hi); }
; __device__ __forceinline__ void transpose_item(const float* W, int K, int N, bf16_t* WT, int drow0, LAS float* scr, int k0, int n0, int lane) {
;     ...
;     asm volatile("s_waitcnt lgkmcnt(0)" ::: "memory");
;     const int c = lane & 7;
; #pragma unroll
;     for (int j = 0; j < 4; ++j) { const int n = (lane >> 3) + 8 * j; const LAS float* s = scr + (8 * c) * 33 + n;
;         u32x4 o; o.x = pk2(s[0 * 33], s[1 * 33]); o.y = pk2(s[2 * 33], s[3 * 33]); o.z = pk2(s[4 * 33], s[5 * 33]); o.w = pk2(s[6 * 33], s[7 * 33]);
;         *(u32x4*)(WT + (size_t)(drow0 + n) * K + k0 + 8 * c) = o; }
;     asm volatile("s_waitcnt lgkmcnt(0)" ::: "memory");
	s_waitcnt lgkmcnt(0)
	ds_read2_b32 v[22:23], v24 offset0:33 offset1:41
	ds_read2_b32 v[32:33], v24 offset1:8
	ds_read2_b32 v[34:35], v24 offset0:66 offset1:74
	ds_read2_b32 v[36:37], v24 offset0:99 offset1:107
	ds_read2_b32 v[38:39], v24 offset0:132 offset1:140
	ds_read2_b32 v[40:41], v24 offset0:165 offset1:173
	ds_read2_b32 v[42:43], v24 offset0:198 offset1:206
	ds_read2_b32 v[44:45], v24 offset0:231 offset1:239
	s_mov_b32 s5, s3
	v_or_b32_e32 v2, s10, v7
	v_lshl_add_u64 v[46:47], s[4:5], 1, v[16:17]
	v_lshlrev_b32_e32 v2, 11, v2
	s_waitcnt lgkmcnt(6)
	v_cvt_pk_bf16_f32 v28, v32, v22
	s_waitcnt lgkmcnt(4)
	v_cvt_pk_bf16_f32 v29, v34, v36
	s_waitcnt lgkmcnt(2)
	v_cvt_pk_bf16_f32 v30, v38, v40
	s_waitcnt lgkmcnt(0)
	v_cvt_pk_bf16_f32 v31, v42, v44
	v_lshl_add_u64 v[48:49], v[46:47], 0, v[2:3]
	global_store_dwordx4 v[48:49], v[28:31], off sc1
	v_or_b32_e32 v2, s10, v25
	v_lshlrev_b32_e32 v2, 11, v2
	v_cvt_pk_bf16_f32 v28, v33, v23
	v_cvt_pk_bf16_f32 v29, v35, v37
	v_cvt_pk_bf16_f32 v30, v39, v41
	v_cvt_pk_bf16_f32 v31, v43, v45
	ds_read2_b32 v[32:33], v24 offset0:49 offset1:57
	ds_read2_b32 v[34:35], v24 offset0:16 offset1:24
	ds_read2_b32 v[36:37], v24 offset0:82 offset1:90
	ds_read2_b32 v[38:39], v24 offset0:115 offset1:123
	ds_read2_b32 v[40:41], v24 offset0:148 offset1:156
	ds_read2_b32 v[42:43], v24 offset0:181 offset1:189
	ds_read2_b32 v[44:45], v24 offset0:214 offset1:222
	ds_read2_b32 v[48:49], v24 offset0:247 offset1:255
	v_lshl_add_u64 v[22:23], v[46:47], 0, v[2:3]
	v_or_b32_e32 v2, s10, v26
	v_lshlrev_b32_e32 v2, 11, v2
	global_store_dwordx4 v[22:23], v[28:31], off sc1
	v_lshl_add_u64 v[22:23], v[46:47], 0, v[2:3]
	v_or_b32_e32 v2, s10, v27
	s_waitcnt lgkmcnt(6)
	v_cvt_pk_bf16_f32 v28, v34, v32
	s_waitcnt lgkmcnt(4)
	v_cvt_pk_bf16_f32 v29, v36, v38
	s_waitcnt lgkmcnt(2)
	v_cvt_pk_bf16_f32 v30, v40, v42
	s_waitcnt lgkmcnt(0)
	v_cvt_pk_bf16_f32 v31, v44, v48
	v_lshlrev_b32_e32 v2, 11, v2
	global_store_dwordx4 v[22:23], v[28:31], off sc1
	v_lshl_add_u64 v[22:23], v[46:47], 0, v[2:3]
	s_nop 0
	v_cvt_pk_bf16_f32 v28, v35, v33
	v_cvt_pk_bf16_f32 v29, v37, v39
	v_cvt_pk_bf16_f32 v30, v41, v43
	v_cvt_pk_bf16_f32 v31, v45, v49
	global_store_dwordx4 v[22:23], v[28:31], off sc1
	s_waitcnt lgkmcnt(0)

; #define LAS __attribute__((address_space(3)))
; __device__ __forceinline__ void transpose_item(const float* W, int K, int N, bf16_t* WT, int drow0, LAS float* scr, int k0, int n0, int lane) {
; #pragma unroll 8
;     for (int i = 0; i < 32; ++i) { const int kk = 2 * i + (lane >> 5); scr[kk * 33 + (lane & 31)] = W[(size_t)(k0 + kk) * N + n0 + (lane & 31)]; }
; __global__ void __launch_bounds__(NTHR, 2) fwd_kernel(Args a) {
;     ...
;     if (bx >= 128) {
;         PHASE_IDS
;         LAS float* scr = (LAS float*)(lds + wave * 16384);
;         for (int r = (bx - 128) * 8 + wave; r < 88 * 64; r += (G - 128) * 8)
;             transpose_item(a.in[I_WDN], FF, DM, WdT, (r % 64) * 32, scr, (r / 64) * 64, (r % 64) * 32, lane);
.LBB0_1810:
	s_lshl_b32 s14, s13, 1
	s_lshl_b32 s15, s12, 1
	v_or_b32_e32 v46, s14, v1
	v_or_b32_e32 v47, s15, v0
	s_add_i32 s16, s14, 4
	s_add_i32 s17, s15, 4
	s_add_i32 s18, s14, 8
	s_add_i32 s19, s15, 8
	s_add_i32 s20, s14, 12
	s_add_i32 s21, s15, 12
	s_add_i32 s22, s14, 16
	s_add_i32 s23, s15, 16
	s_add_i32 s24, s14, 20
	s_add_i32 s25, s15, 20
	s_add_i32 s26, s14, 24
	s_add_i32 s27, s15, 24
	s_add_i32 s14, s14, 28
	s_add_i32 s15, s15, 28
	v_add_u32_e32 v16, s6, v47
	v_or_b32_e32 v48, s16, v1
	v_or_b32_e32 v49, s17, v0
	v_or_b32_e32 v50, s18, v1
	v_or_b32_e32 v51, s19, v0
	v_or_b32_e32 v52, s20, v1
	v_or_b32_e32 v53, s21, v0
	v_or_b32_e32 v54, s22, v1
	v_or_b32_e32 v55, s23, v0
	v_or_b32_e32 v56, s24, v1
	v_or_b32_e32 v57, s25, v0
	v_or_b32_e32 v58, s26, v1
	v_or_b32_e32 v59, s27, v0
	v_or_b32_e32 v60, s14, v1
	v_or_b32_e32 v61, s15, v0
	v_add_u32_e32 v14, s3, v46
	v_ashrrev_i32_e32 v17, 31, v16
	v_add_u32_e32 v18, s3, v48
	v_add_u32_e32 v20, s6, v49
	v_add_u32_e32 v22, s3, v50
	v_add_u32_e32 v24, s6, v51
	v_add_u32_e32 v26, s3, v52
	v_add_u32_e32 v28, s6, v53
	v_add_u32_e32 v30, s3, v54
	v_add_u32_e32 v32, s6, v55
	v_add_u32_e32 v34, s3, v56
	v_add_u32_e32 v36, s6, v57
	v_add_u32_e32 v38, s3, v58
	v_add_u32_e32 v40, s6, v59
	v_add_u32_e32 v42, s3, v60
	v_add_u32_e32 v44, s6, v61
	v_ashrrev_i32_e32 v15, 31, v14
	v_lshlrev_b64 v[16:17], 13, v[16:17]
	v_ashrrev_i32_e32 v21, 31, v20
	v_ashrrev_i32_e32 v19, 31, v18
	v_ashrrev_i32_e32 v25, 31, v24
	v_ashrrev_i32_e32 v23, 31, v22
	v_ashrrev_i32_e32 v29, 31, v28
	v_ashrrev_i32_e32 v27, 31, v26
	v_ashrrev_i32_e32 v33, 31, v32
	v_ashrrev_i32_e32 v31, 31, v30
	v_ashrrev_i32_e32 v37, 31, v36
	v_ashrrev_i32_e32 v35, 31, v34
	v_ashrrev_i32_e32 v41, 31, v40
	v_ashrrev_i32_e32 v39, 31, v38
	v_ashrrev_i32_e32 v45, 31, v44
	v_ashrrev_i32_e32 v43, 31, v42
	v_lshlrev_b64 v[14:15], 13, v[14:15]
	v_lshl_add_u64 v[16:17], v[8:9], 0, v[16:17]
	v_lshlrev_b64 v[18:19], 13, v[18:19]
	v_lshlrev_b64 v[20:21], 13, v[20:21]
	v_lshlrev_b64 v[22:23], 13, v[22:23]
	v_lshlrev_b64 v[24:25], 13, v[24:25]
	v_lshlrev_b64 v[26:27], 13, v[26:27]
	v_lshlrev_b64 v[28:29], 13, v[28:29]
	v_lshlrev_b64 v[30:31], 13, v[30:31]
	v_lshlrev_b64 v[32:33], 13, v[32:33]
	v_lshlrev_b64 v[34:35], 13, v[34:35]
	v_lshlrev_b64 v[36:37], 13, v[36:37]
	v_lshlrev_b64 v[38:39], 13, v[38:39]
	v_lshlrev_b64 v[40:41], 13, v[40:41]
	v_lshlrev_b64 v[42:43], 13, v[42:43]
	v_lshlrev_b64 v[44:45], 13, v[44:45]
	v_lshl_add_u64 v[14:15], v[8:9], 0, v[14:15]
	v_lshl_add_u64 v[20:21], v[8:9], 0, v[20:21]
	v_lshl_add_u64 v[18:19], v[8:9], 0, v[18:19]
	v_lshl_add_u64 v[24:25], v[8:9], 0, v[24:25]
	v_lshl_add_u64 v[22:23], v[8:9], 0, v[22:23]
	v_lshl_add_u64 v[28:29], v[8:9], 0, v[28:29]
	v_lshl_add_u64 v[26:27], v[8:9], 0, v[26:27]
	v_lshl_add_u64 v[32:33], v[8:9], 0, v[32:33]
	v_lshl_add_u64 v[30:31], v[8:9], 0, v[30:31]
	v_lshl_add_u64 v[36:37], v[8:9], 0, v[36:37]
	v_lshl_add_u64 v[34:35], v[8:9], 0, v[34:35]
	v_lshl_add_u64 v[40:41], v[8:9], 0, v[40:41]
	v_lshl_add_u64 v[38:39], v[8:9], 0, v[38:39]
	v_lshl_add_u64 v[44:45], v[8:9], 0, v[44:45]
	v_lshl_add_u64 v[42:43], v[8:9], 0, v[42:43]
	global_load_dword v62, v[16:17], off nt
	global_load_dword v63, v[14:15], off nt
	global_load_dword v64, v[20:21], off nt
	global_load_dword v65, v[18:19], off nt
	global_load_dword v66, v[24:25], off nt
	global_load_dword v67, v[22:23], off nt
	global_load_dword v68, v[28:29], off nt
	global_load_dword v69, v[26:27], off nt
	global_load_dword v70, v[32:33], off nt
	global_load_dword v71, v[30:31], off nt
	global_load_dword v72, v[36:37], off nt
	global_load_dword v73, v[34:35], off nt
	global_load_dword v74, v[40:41], off nt
	global_load_dword v75, v[38:39], off nt
	global_load_dword v76, v[44:45], off nt
	global_load_dword v77, v[42:43], off nt
	s_add_i32 s12, s12, 16
	s_add_i32 s13, s13, 16
	s_add_i32 s7, s7, -16
	v_mad_u64_u32 v[14:15], s[14:15], v47, s9, v[4:5]
	s_cmp_lg_u32 s7, 0
	v_mad_u64_u32 v[16:17], s[14:15], v46, s9, v[4:5]
	v_mad_u64_u32 v[18:19], s[14:15], v49, s9, v[4:5]
	v_mad_u64_u32 v[20:21], s[14:15], v48, s9, v[4:5]
	v_mad_u64_u32 v[22:23], s[14:15], v51, s9, v[4:5]
	v_mad_u64_u32 v[24:25], s[14:15], v50, s9, v[4:5]
	v_mad_u64_u32 v[26:27], s[14:15], v53, s9, v[4:5]
	v_mad_u64_u32 v[28:29], s[14:15], v52, s9, v[4:5]
	v_mad_u64_u32 v[30:31], s[14:15], v55, s9, v[4:5]
	v_mad_u64_u32 v[32:33], s[14:15], v54, s9, v[4:5]
	v_mad_u64_u32 v[34:35], s[14:15], v57, s9, v[4:5]
	v_mad_u64_u32 v[36:37], s[14:15], v56, s9, v[4:5]
	v_mad_u64_u32 v[38:39], s[14:15], v59, s9, v[4:5]
	v_mad_u64_u32 v[40:41], s[14:15], v58, s9, v[4:5]
	v_mad_u64_u32 v[42:43], s[14:15], v61, s9, v[4:5]
	v_mad_u64_u32 v[44:45], s[14:15], v60, s9, v[4:5]
	s_waitcnt vmcnt(15)
	ds_write_b32 v14, v62
	s_waitcnt vmcnt(14)
	ds_write_b32 v16, v63
	s_waitcnt vmcnt(13)
	ds_write_b32 v18, v64
	s_waitcnt vmcnt(12)
	ds_write_b32 v20, v65
	s_waitcnt vmcnt(11)
	ds_write_b32 v22, v66
	s_waitcnt vmcnt(10)
	ds_write_b32 v24, v67
	s_waitcnt vmcnt(9)
	ds_write_b32 v26, v68
	s_waitcnt vmcnt(8)
	ds_write_b32 v28, v69
	s_waitcnt vmcnt(7)
	ds_write_b32 v30, v70
	s_waitcnt vmcnt(6)
	ds_write_b32 v32, v71
	s_waitcnt vmcnt(5)
	ds_write_b32 v34, v72
	s_waitcnt vmcnt(4)
	ds_write_b32 v36, v73
	s_waitcnt vmcnt(3)
	ds_write_b32 v38, v74
	s_waitcnt vmcnt(2)
	ds_write_b32 v40, v75
	s_waitcnt vmcnt(1)
	ds_write_b32 v42, v76
	s_waitcnt vmcnt(0)
	ds_write_b32 v44, v77
	s_cbranch_scc1 .LBB0_1810
; #define LAS __attribute__((address_space(3)))
; __device__ __forceinline__ unsigned pk2(float lo, float hi) { return pk2hw(lo, hi); }
; __device__ __forceinline__ void transpose_item(const float* W, int K, int N, bf16_t* WT, int drow0, LAS float* scr, int k0, int n0, int lane) {
;     ...
;     asm volatile("s_waitcnt lgkmcnt(0)" ::: "memory");
;     const int c = lane & 7;
; #pragma unroll
;     for (int j = 0; j < 4; ++j) { const int n = (lane >> 3) + 8 * j; const LAS float* s = scr + (8 * c) * 33 + n;
;         u32x4 o; o.x = pk2(s[0 * 33], s[1 * 33]); o.y = pk2(s[2 * 33], s[3 * 33]); o.z = pk2(s[4 * 33], s[5 * 33]); o.w = pk2(s[6 * 33], s[7 * 33]);
;         *(u32x4*)(WT + (size_t)(drow0 + n) * K + k0 + 8 * c) = o; }
;     asm volatile("s_waitcnt lgkmcnt(0)" ::: "memory");
; __global__ void __launch_bounds__(NTHR, 2) fwd_kernel(Args a) {
;     ...
;         for (int r = (bx - 128) * 8 + wave; r < 88 * 64; r += (G - 128) * 8)
	s_waitcnt lgkmcnt(0)
	ds_read2_b32 v[8:9], v10 offset0:33 offset1:41
	ds_read2_b32 v[18:19], v10 offset1:8
	ds_read2_b32 v[20:21], v10 offset0:66 offset1:74
	ds_read2_b32 v[22:23], v10 offset0:99 offset1:107
	ds_read2_b32 v[24:25], v10 offset0:132 offset1:140
	ds_read2_b32 v[26:27], v10 offset0:165 offset1:173
	ds_read2_b32 v[28:29], v10 offset0:198 offset1:206
	ds_read2_b32 v[30:31], v10 offset0:231 offset1:239
	s_waitcnt lgkmcnt(6)
	v_cvt_pk_bf16_f32 v14, v18, v8
	v_or_b32_e32 v8, s2, v5
	s_ashr_i32 s7, s6, 31
	v_mul_lo_u32 v34, v8, s11
	v_lshl_add_u64 v[32:33], s[6:7], 1, v[6:7]
	v_ashrrev_i32_e32 v35, 31, v34
	s_waitcnt lgkmcnt(4)
	v_cvt_pk_bf16_f32 v15, v20, v22
	s_waitcnt lgkmcnt(2)
	v_cvt_pk_bf16_f32 v16, v24, v26
	s_waitcnt lgkmcnt(0)
	v_cvt_pk_bf16_f32 v17, v28, v30
	v_lshl_add_u64 v[34:35], v[34:35], 1, v[32:33]
	v_or_b32_e32 v8, s2, v11
	global_store_dwordx4 v[34:35], v[14:17], off sc1
	v_mul_lo_u32 v8, v8, s11
	s_add_i32 s8, s10, s8
	v_cvt_pk_bf16_f32 v14, v19, v9
	v_cvt_pk_bf16_f32 v15, v21, v23
	v_cvt_pk_bf16_f32 v16, v25, v27
	v_cvt_pk_bf16_f32 v17, v29, v31
	v_ashrrev_i32_e32 v9, 31, v8
	ds_read2_b32 v[18:19], v10 offset0:49 offset1:57
	ds_read2_b32 v[20:21], v10 offset0:16 offset1:24
	ds_read2_b32 v[22:23], v10 offset0:82 offset1:90
	ds_read2_b32 v[24:25], v10 offset0:115 offset1:123
	ds_read2_b32 v[26:27], v10 offset0:148 offset1:156
	ds_read2_b32 v[28:29], v10 offset0:181 offset1:189
	ds_read2_b32 v[30:31], v10 offset0:214 offset1:222
	ds_read2_b32 v[34:35], v10 offset0:247 offset1:255
	v_lshl_add_u64 v[8:9], v[8:9], 1, v[32:33]
	global_store_dwordx4 v[8:9], v[14:17], off sc1
	v_or_b32_e32 v8, s2, v12
	v_mul_lo_u32 v8, v8, s11
	v_ashrrev_i32_e32 v9, 31, v8
	s_waitcnt lgkmcnt(6)
	v_cvt_pk_bf16_f32 v14, v20, v18
	s_waitcnt lgkmcnt(4)
	v_cvt_pk_bf16_f32 v15, v22, v24
	s_waitcnt lgkmcnt(2)
	v_cvt_pk_bf16_f32 v16, v26, v28
	s_waitcnt lgkmcnt(0)
	v_cvt_pk_bf16_f32 v17, v30, v34
	v_lshl_add_u64 v[8:9], v[8:9], 1, v[32:33]
	global_store_dwordx4 v[8:9], v[14:17], off sc1
	v_or_b32_e32 v8, s2, v13
	v_mul_lo_u32 v8, v8, s11
	v_ashrrev_i32_e32 v9, 31, v8
	v_cvt_pk_bf16_f32 v14, v21, v19
	v_cvt_pk_bf16_f32 v15, v23, v25
	v_cvt_pk_bf16_f32 v16, v27, v29
	v_cvt_pk_bf16_f32 v17, v31, v35
	v_lshl_add_u64 v[8:9], v[8:9], 1, v[32:33]
	global_store_dwordx4 v[8:9], v[14:17], off sc1
	s_waitcnt lgkmcnt(0)
	s_cmpk_lt_i32 s8, 0x1600
	s_cbranch_scc1 .LBB0_1809
